# peel + removed redundant acquire fence (buffer_inv sc1) in the LayerNorm stats exchange (all subsequent cross-WG reads are sc1 loads)
# speedup vs baseline: 1.0100x; 1.0100x over previous
.LBB0_966:
	s_and_saveexec_b64 s[14:15], s[42:43]
	s_cbranch_execz .LBB0_969
	s_waitcnt vmcnt(0)
	s_and_b64 exec, exec, s[40:41]
	s_cbranch_execz .LBB0_969
	v_readlane_b32 s21, v255, 8
	s_nop 1
	v_mov_b32_e32 v209, s21
	ds_write_b32 v209, v0

.LBB0_1895:
	s_and_saveexec_b64 s[10:11], s[12:13]
	s_cbranch_execz .LBB0_1898
	s_waitcnt vmcnt(0)
	s_and_b64 exec, exec, s[40:41]
	s_cbranch_execz .LBB0_1898
	v_readlane_b32 s12, v255, 8
	s_nop 1
	v_mov_b32_e32 v197, s12
	ds_write_b32 v197, v0
